# grid barrier: the first workgroup of an XCD to arrive starts an L2 writeback early (the leader's later writeback then has less to flush)
# speedup vs baseline: 1.0030x; 1.0030x over previous
.LBB0_963:
	s_or_b64 exec, exec, s[2:3]
	v_cvt_f32_u32_e32 v4, v2
	s_waitcnt vmcnt(0)
	v_readfirstlane_b32 s2, v3
	v_sub_u32_e32 v3, 0, v2
	v_rcp_iflag_f32_e32 v4, v4
	v_add_u32_e32 v5, s2, v1
	v_mul_f32_e32 v4, 0x4f7ffffe, v4
	v_cvt_u32_f32_e32 v4, v4
	v_mul_lo_u32 v1, v3, v4
	v_mul_hi_u32 v1, v4, v1
	v_add_u32_e32 v1, v4, v1
	v_mul_hi_u32 v1, v5, v1
	v_mul_lo_u32 v3, v1, v2
	v_sub_u32_e32 v3, v5, v3
	v_add_u32_e32 v4, 1, v1
	v_cmp_ge_u32_e32 vcc, v3, v2
	s_nop 1
	v_cndmask_b32_e32 v1, v1, v4, vcc
	v_sub_u32_e32 v4, v3, v2
	v_cndmask_b32_e32 v3, v3, v4, vcc
	v_add_u32_e32 v4, 1, v1
	v_cmp_ge_u32_e32 vcc, v3, v2
	v_add_u32_e32 v3, 1, v5
	s_nop 0
	v_cndmask_b32_e32 v1, v1, v4, vcc
	v_mul_lo_u32 v4, v2, v1
	v_add_u32_e32 v2, v4, v2
	v_cmp_ne_u32_e32 vcc, v3, v2
	s_and_saveexec_b64 s[2:3], vcc
	s_xor_b64 s[2:3], exec, s[2:3]
	s_cbranch_execz .LBB0_977
	v_cmp_eq_u32_e32 vcc, v5, v4
	s_cbranch_vccz .Lbar_nopre
	buffer_wbl2 sc1
.Lbar_nopre:
	v_readlane_b32 s6, v253, 43
	v_readlane_b32 s7, v253, 44
	s_waitcnt lgkmcnt(0)
	s_nop 3
	global_load_dword v0, v65, s[6:7] sc1
	s_waitcnt vmcnt(0)
	v_cmp_eq_u32_e32 vcc, v0, v1
	s_and_saveexec_b64 s[22:23], vcc
	s_cbranch_execz .LBB0_976
	s_mov_b32 s5, 1
	s_mov_b64 s[28:29], 0
	s_branch .LBB0_967
